# attention loop: masked V write and loop bookkeeping issued before the last P.V MFMA (on v43)
# speedup vs baseline: 1.0135x; 1.0060x over previous
; template <int DQK, bool MLA> ...
;     ...
;     auto substep = [&](f32x16& a, f32x16& b, int knext_ofs, int vofs, int h, int kafter_ofs) __attribute__((always_inline)) {
;         const LAS unsigned char* kb = lds + knext_ofs + r32 * KPITCH + hi * 16;
;         const LAS unsigned char* vb = lds + vofs + r32 * 144 + hi * 16 + h * 64;
;         u32x4 pw0, pw1; bf16x8 vf0[4], vf1[4], kr[3];
;         kr[0] = kp0; kr[1] = kp1;
;         float rs0 = rs_early;
;         __builtin_amdgcn_sched_barrier(0);
; #pragma unroll
;         for (int d0 = 0; d0 < KS; ++d0) {
;             if (d0 + 2 < KS) kr[(d0 + 2) % 3] = *(const LAS bf16x8*)(kb + (d0 + 2) * 32);
;             if (d0 == KS - 3) {
; #pragma unroll
;                 for (int d = 0; d < 4; ++d) vf0[d] = *(const LAS bf16x8*)(vb + d * 4608);
;             }
;             if (d0 == 0) { const f32x16 z16 = {0.f, 0.f, 0.f, 0.f, 0.f, 0.f, 0.f, 0.f, 0.f, 0.f, 0.f, 0.f, 0.f, 0.f, 0.f, 0.f};
;                 b = __builtin_amdgcn_mfma_f32_32x32x16_bf16(kr[0], qf[0], z16, 0, 0, 0); }
;             else b = __builtin_amdgcn_mfma_f32_32x32x16_bf16(kr[d0 % 3], qf[d0], b, 0, 0, 0);
; #pragma unroll
;             for (int e = 6 + (10 * d0) / KS; e < 6 + (10 * (d0 + 1)) / KS; ++e) {
;                 const float x = __builtin_amdgcn_exp2f(a[e]);
;                 a[e] = x;
;                 rs0 += x;
;                 if (e == 7)  { pw0.x = pk(a[0], a[1]); pw0.y = pk(a[2], a[3]);   pw0.z = pk(a[4], a[5]);   pw0.w = pk(a[6], a[7]); }
;                 if (e == 15) { pw1.x = pk(a[8], a[9]); pw1.y = pk(a[10], a[11]); pw1.z = pk(a[12], a[13]); pw1.w = pk(a[14], a[15]); }
;             }
;             __builtin_amdgcn_sched_barrier(0);
;         }
;         l_run += rs0;
;         float rs_n = 0.f;
; #pragma unroll
;         for (int kk = 0; kk < 2; ++kk) {
;             if (kk == 0) {
; #pragma unroll
;                 for (int d = 0; d < 4; ++d) vf1[d] = *(const LAS bf16x8*)(vb + d * 4608 + 32);
;             } else { const LAS unsigned char* ka = lds + kafter_ofs + r32 * KPITCH + hi * 16; kp0 = *(const LAS bf16x8*)(ka); kp1 = *(const LAS bf16x8*)(ka + 32); }
;             const bf16x8 pb = __builtin_bit_cast(bf16x8, kk ? pw1 : pw0);
; #pragma unroll
;             for (int d = 0; d < 4; ++d) {
;                 o[d] = __builtin_amdgcn_mfma_f32_32x32x16_bf16(kk ? vf1[d] : vf0[d], pb, o[d], 0, 0, 0);
.Lattn_ld6_skip:
	s_or_b64 exec, exec, s[34:35]
	ds_read_b128 v[160:163], v193 offset:13024
	v_exp_f32_e32 v195, v74
	s_nop 0
	v_add_f32_e32 v72, v195, v72
	v_lshl_add_u64 v[190:191], v[190:191], 0, s[20:21]
	s_waitcnt lgkmcnt(1)
	v_mfma_f32_32x32x16_bf16 v[80:95], v[210:213], v[124:127], v[80:95]
	ds_read_b128 v[68:71], v193 offset:13056
	s_waitcnt lgkmcnt(1)
	v_mfma_f32_32x32x16_bf16 v[80:95], v[160:163], v[128:131], v[80:95]
	v_exp_f32_e32 v196, v75
	ds_read_b128 v[210:213], v193 offset:13088
	v_add_f32_e32 v160, v196, v72
	s_waitcnt lgkmcnt(1)
	v_mfma_f32_32x32x16_bf16 v[80:95], v[68:71], v[136:139], v[80:95]
	ds_read_b128 v[72:75], v193 offset:13120
	v_exp_f32_e32 v76, v76
	s_nop 0
	v_add_f32_e32 v197, v76, v160
	ds_read_b128 v[68:71], v193 offset:13152
	ds_read_b128 v[160:163], v208
	ds_read_b128 v[214:217], v208 offset:4608
	ds_read_b128 v[218:221], v208 offset:9216
	ds_read_b128 v[222:225], v208 offset:13824
	s_waitcnt lgkmcnt(6)
	v_mfma_f32_32x32x16_bf16 v[80:95], v[210:213], v[144:147], v[80:95]
	v_exp_f32_e32 v77, v77
	s_nop 0
	v_add_f32_e32 v193, v77, v197
	s_waitcnt lgkmcnt(5)
	v_mfma_f32_32x32x16_bf16 v[80:95], v[72:75], v[132:135], v[80:95]
	v_exp_f32_e32 v72, v78
	s_nop 0
	v_add_f32_e32 v73, v72, v193
	s_waitcnt lgkmcnt(4)
	v_mfma_f32_32x32x16_bf16 v[80:95], v[68:71], v[140:143], v[80:95]
	v_exp_f32_e32 v71, v79
	v_cvt_pk_bf16_f32 v68, v194, v186
	v_cvt_pk_bf16_f32 v69, v195, v196
	v_cvt_pk_bf16_f32 v70, v76, v77
	v_add_f32_e32 v73, v71, v73
	v_cvt_pk_bf16_f32 v71, v72, v71
	s_waitcnt lgkmcnt(3)
	v_mfma_f32_32x32x16_bf16 v[48:63], v[160:163], v[64:67], v[48:63]
	v_add_f32_e32 v187, v187, v73
	ds_read_b128 v[72:75], v208 offset:32
	ds_read_b128 v[76:79], v208 offset:4640
	ds_read_b128 v[160:163], v208 offset:9248
	ds_read_b128 v[210:213], v208 offset:13856
	s_nop 1
	v_exp_f32_e32 v186, v80
	v_exp_f32_e32 v193, v81
	s_waitcnt lgkmcnt(6)
	v_mfma_f32_32x32x16_bf16 v[32:47], v[214:217], v[64:67], v[32:47]
	s_waitcnt lgkmcnt(5)
	v_mfma_f32_32x32x16_bf16 v[16:31], v[218:221], v[64:67], v[16:31]
	s_waitcnt lgkmcnt(4)
	v_mfma_f32_32x32x16_bf16 v[0:15], v[222:225], v[64:67], v[0:15]
	s_waitcnt lgkmcnt(3)
	v_mfma_f32_32x32x16_bf16 v[48:63], v[72:75], v[68:71], v[48:63]
	v_exp_f32_e32 v195, v82
	v_add_u32_e32 v194, s72, v183
	v_exp_f32_e32 v196, v83
	ds_read_b128 v[64:67], v194
	ds_read_b128 v[214:217], v194 offset:32
	v_exp_f32_e32 v84, v84
	v_add_f32_e32 v72, 0, v186
	v_exp_f32_e32 v85, v85
	s_waitcnt lgkmcnt(4)
	v_mfma_f32_32x32x16_bf16 v[32:47], v[76:79], v[68:71], v[32:47]
	v_add_f32_e32 v72, v193, v72
	v_add_f32_e32 v72, v195, v72
	v_add_f32_e32 v72, v196, v72
	v_add_f32_e32 v72, v84, v72
	v_add_f32_e32 v197, v85, v72
	s_waitcnt lgkmcnt(3)
	v_mfma_f32_32x32x16_bf16 v[16:31], v[160:163], v[68:71], v[16:31]
	s_waitcnt lgkmcnt(2)
	v_mfma_f32_32x32x16_bf16 v[0:15], v[210:213], v[68:71], v[0:15]
	s_waitcnt lgkmcnt(1)
	v_mfma_f32_32x32x16_bf16 v[64:79], v[64:67], v[100:103], 0
	ds_read_b128 v[80:83], v194 offset:64
	s_waitcnt lgkmcnt(1)
	v_mfma_f32_32x32x16_bf16 v[64:79], v[214:217], v[104:107], v[64:79]
	ds_read_b128 v[160:163], v194 offset:96
	v_exp_f32_e32 v86, v86
	s_nop 0
	v_add_f32_e32 v197, v86, v197
	s_waitcnt lgkmcnt(1)
	v_mfma_f32_32x32x16_bf16 v[64:79], v[80:83], v[108:111], v[64:79]
	ds_read_b128 v[210:213], v194 offset:128
	v_exp_f32_e32 v83, v87
	v_cvt_pk_bf16_f32 v80, v186, v193
	v_cvt_pk_bf16_f32 v81, v195, v196
	v_cvt_pk_bf16_f32 v82, v84, v85
	v_add_f32_e32 v197, v83, v197
	v_cvt_pk_bf16_f32 v83, v86, v83
	s_waitcnt lgkmcnt(1)
	v_mfma_f32_32x32x16_bf16 v[64:79], v[160:163], v[112:115], v[64:79]
	ds_read_b128 v[84:87], v194 offset:160
	v_exp_f32_e32 v186, v88
	s_nop 0
	v_add_f32_e32 v88, v186, v197
	s_waitcnt lgkmcnt(1)
; #define LAS __attribute__((address_space(3)))
; template <int DQK, bool MLA> ...
;     ...
; #pragma unroll
;         for (int kk = 0; kk < 2; ++kk) {
;             if (kk == 0) {
; #pragma unroll
;                 for (int d = 0; d < 4; ++d) vf1[d] = *(const LAS bf16x8*)(vb + d * 4608 + 32);
;             } else { const LAS unsigned char* ka = lds + kafter_ofs + r32 * KPITCH + hi * 16; kp0 = *(const LAS bf16x8*)(ka); kp1 = *(const LAS bf16x8*)(ka + 32); }
;             const bf16x8 pb = __builtin_bit_cast(bf16x8, kk ? pw1 : pw0);
; #pragma unroll
;             for (int d = 0; d < 4; ++d) {
;                 o[d] = __builtin_amdgcn_mfma_f32_32x32x16_bf16(kk ? vf1[d] : vf0[d], pb, o[d], 0, 0, 0);
;                 const int e = 4 * kk + d - 2;
;                 if (e >= 0) { const float x = __builtin_amdgcn_exp2f(b[e]); b[e] = x; rs_n += x; }
;             }
;             __builtin_amdgcn_sched_barrier(0);
;         }
;         rs_early = rs_n;
;     };
;     int kc = 0, kn = KT_BYTES, kn2 = 2 * KT_BYTES;
;     for (int t = 0; t < NT; ++t) {
;         const bool has_k2 = (t + 2 < NT), has_v1 = (t + 1 < NT), active = (t <= tmax_w);
;         const int vofs = 3 * KT_BYTES + (t & 1) * VT_BYTES;
;         if (has_k2) gload_k(t + 2);
;         if (has_v1) gload_v(t + 1);
;         if (active) substep(sX, sY, kc + 32 * KPITCH, vofs, 0, kn);
;         if (active) substep(sY, sX, kn, vofs, 1, kn + 32 * KPITCH);
;         if (has_k2) sts_k(kn2);
;         if (has_v1) sts_v((t + 1) & 1);
;         __syncthreads();
;         const int tmp = kc; kc = kn; kn = kn2; kn2 = tmp;
	v_mfma_f32_32x32x16_bf16 v[64:79], v[210:213], v[116:119], v[64:79]
	ds_read_b128 v[160:163], v194 offset:192
	v_exp_f32_e32 v196, v89
	s_nop 0
	v_add_f32_e32 v88, v196, v88
	s_waitcnt lgkmcnt(1)
	v_mfma_f32_32x32x16_bf16 v[64:79], v[84:87], v[120:123], v[64:79]
	ds_read_b128 v[210:213], v194 offset:224
	v_exp_f32_e32 v226, v90
	s_nop 0
	v_add_f32_e32 v193, v226, v88
	s_waitcnt lgkmcnt(1)
	v_mfma_f32_32x32x16_bf16 v[64:79], v[160:163], v[124:127], v[64:79]
	ds_read_b128 v[84:87], v194 offset:256
	s_waitcnt lgkmcnt(1)
	v_mfma_f32_32x32x16_bf16 v[64:79], v[210:213], v[128:131], v[64:79]
	ds_read_b128 v[160:163], v194 offset:288
	v_exp_f32_e32 v195, v91
	s_waitcnt lgkmcnt(1)
	v_mfma_f32_32x32x16_bf16 v[64:79], v[84:87], v[136:139], v[64:79]
	ds_read_b128 v[88:91], v194 offset:320
	v_exp_f32_e32 v197, v92
	ds_read_b128 v[84:87], v194 offset:352
	ds_read_b128 v[210:213], v208 offset:64
	ds_read_b128 v[214:217], v208 offset:4672
	ds_read_b128 v[218:221], v208 offset:9280
	ds_read_b128 v[222:225], v208 offset:13888
	s_waitcnt lgkmcnt(6)
	v_mfma_f32_32x32x16_bf16 v[64:79], v[160:163], v[144:147], v[64:79]
	v_exp_f32_e32 v209, v93
	s_waitcnt lgkmcnt(5)
	v_mfma_f32_32x32x16_bf16 v[64:79], v[88:91], v[132:135], v[64:79]
	v_exp_f32_e32 v227, v94
	s_waitcnt lgkmcnt(4)
	v_mfma_f32_32x32x16_bf16 v[64:79], v[84:87], v[140:143], v[64:79]
	v_exp_f32_e32 v229, v95
	v_cvt_pk_bf16_f32 v84, v186, v196
	v_cvt_pk_bf16_f32 v85, v226, v195
	v_cvt_pk_bf16_f32 v86, v197, v209
	v_cvt_pk_bf16_f32 v87, v227, v229
	s_waitcnt lgkmcnt(3)
	v_mfma_f32_32x32x16_bf16 v[48:63], v[210:213], v[80:83], v[48:63]
	s_add_i32 s98, s68, 1
	s_bitcmp1_b32 s98, 0
	s_cselect_b32 s98, 0x4800, 0
	v_add_u32_e32 v230, s71, v172
	v_add_u32_e32 v231, s71, v174
	v_add_u32_e32 v232, s71, v184
	v_add_u32_e32 v233, s98, v173
	s_waitcnt vmcnt(4)
	ds_write_b128 v230, v[148:151]
	v_exp_f32_e32 v64, v64
	v_exp_f32_e32 v65, v65
	s_waitcnt lgkmcnt(3)
	v_mfma_f32_32x32x16_bf16 v[32:47], v[214:217], v[80:83], v[32:47]
	ds_read_b128 v[88:91], v208 offset:96
	ds_read_b128 v[92:95], v208 offset:4704
	ds_read_b128 v[210:213], v208 offset:9312
	ds_read_b128 v[214:217], v208 offset:13920
	s_waitcnt lgkmcnt(6)
	v_mfma_f32_32x32x16_bf16 v[16:31], v[218:221], v[80:83], v[16:31]
	s_waitcnt vmcnt(3)
	ds_write_b128 v231, v[152:155]
	s_waitcnt lgkmcnt(6)
	v_mfma_f32_32x32x16_bf16 v[0:15], v[222:225], v[80:83], v[0:15]
	v_exp_f32_e32 v66, v66
	s_waitcnt vmcnt(2)
	ds_write_b128 v232, v[156:159] offset:256
	s_waitcnt lgkmcnt(5)
	v_mfma_f32_32x32x16_bf16 v[48:63], v[88:91], v[84:87], v[48:63]
	v_exp_f32_e32 v67, v67
	ds_read_b128 v[80:83], v194 offset:12800
	ds_read_b128 v[160:163], v194 offset:12832
	v_exp_f32_e32 v68, v68
	v_mov_b32_e32 v194, v64
	v_exp_f32_e32 v69, v69
	v_pk_add_f32 v[88:89], v[194:195], v[192:193]
	v_mov_b32_e32 v196, v65
	s_waitcnt lgkmcnt(6)
	v_mfma_f32_32x32x16_bf16 v[32:47], v[92:95], v[84:87], v[32:47]
	v_add_f32_e64 v88, v196, v88
	v_add_f32_e64 v89, v197, v89
	v_mov_b32_e32 v208, v66
	v_add_f32_e64 v88, v208, v88
	v_add_f32_e64 v89, v209, v89
	v_mov_b32_e32 v226, v67
	v_pk_add_f32 v[88:89], v[226:227], v[88:89]
	v_mov_b32_e32 v228, v68
	v_pk_add_f32 v[88:89], v[228:229], v[88:89]
	s_waitcnt vmcnt(1)
	ds_write_b128 v233, v[164:167]
	s_waitcnt lgkmcnt(6)
	v_mfma_f32_32x32x16_bf16 v[16:31], v[210:213], v[84:87], v[16:31]
	s_waitcnt vmcnt(0)
	s_add_i32 s68, s68, 1
	s_add_i32 s73, s71, 0
	s_bitcmp1_b32 s68, 0
	s_cselect_b64 s[34:35], -1, 0
	s_and_b64 s[66:67], s[34:35], exec
	s_cselect_b32 s66, 0x4800, 0
	s_and_saveexec_b64 s[66:67], s[4:5]
	ds_write_b128 v233, v[96:99] offset:16384
	s_or_b64 exec, exec, s[66:67]
	ds_write_b128 v233, v[168:171] offset:8192
	v_mov_b32_e32 v186, v69
	v_add_f32_e64 v186, v186, v88
	v_add_f32_e64 v187, v187, v89
	s_waitcnt lgkmcnt(7)
	v_mfma_f32_32x32x16_bf16 v[0:15], v[214:217], v[84:87], v[0:15]
	s_branch .Lattn_wtail
